# LayerNorm row loops: 2-deep prefetch, counted vmcnt, DPP wave reductions instead of ds_bpermute
# speedup vs baseline: 1.0061x; 1.0061x over previous
.LBB0_629:
	s_or_b64 exec, exec, s[0:1]
	s_mov_b64 s[4:5], s[94:95]
	s_mov_b64 s[0:1], s[36:37]
	s_waitcnt lgkmcnt(0)
	s_barrier
	v_mov_b32_e32 v0, v154
	v_readlane_b32 s4, v255, 20
	v_readlane_b32 s5, v255, 21
	v_and_b32_e32 v33, 63, v0
	v_readlane_b32 s6, v255, 22
	v_readlane_b32 s7, v255, 23
	v_readlane_b32 s8, v255, 24
	v_readlane_b32 s9, v255, 25
	v_mov_b32_e32 v32, v154
	v_lshlrev_b32_e32 v34, 4, v33
	v_readlane_b32 s10, v255, 26
	v_readlane_b32 s11, v255, 27
	s_mov_b64 s[4:5], s[8:9]
	s_mov_b64 s[6:7], s[10:11]
	global_load_dwordx4 v[0:3], v34, s[4:5]
	global_load_dwordx4 v[4:7], v34, s[6:7]
	global_load_dwordx4 v[8:11], v34, s[4:5] offset:1024
	global_load_dwordx4 v[12:15], v34, s[6:7] offset:1024
	global_load_dwordx4 v[16:19], v34, s[4:5] offset:2048
	global_load_dwordx4 v[20:23], v34, s[6:7] offset:2048
	global_load_dwordx4 v[24:27], v34, s[4:5] offset:3072
	global_load_dwordx4 v[28:31], v34, s[6:7] offset:3072
	v_readlane_b32 s2, v255, 0
	v_ashrrev_i32_e32 v32, 6, v32
	v_readlane_b32 s12, v255, 28
	v_lshl_add_u32 v32, s2, 3, v32
	s_mov_b32 s2, 0x8400
	v_cmp_gt_i32_e32 vcc, s2, v32
	v_readlane_b32 s13, v255, 29
	v_readlane_b32 s14, v255, 30
	v_readlane_b32 s15, v255, 31
	v_readlane_b32 s16, v255, 32
	v_readlane_b32 s17, v255, 33
	v_readlane_b32 s18, v255, 34
	v_readlane_b32 s19, v255, 35
	s_and_saveexec_b64 s[4:5], vcc
	s_cbranch_execz .LBB0_632
	v_xor_b32_e32 v34, 1, v155
	v_cmp_lt_i32_e32 vcc, v34, v156
	v_mov_b32_e32 v35, 0
	s_lshl_b32 s2, s84, 3
	v_cndmask_b32_e32 v34, v155, v34, vcc
	v_lshlrev_b32_e32 v38, 2, v34
	v_xor_b32_e32 v34, 2, v155
	v_cmp_lt_i32_e32 vcc, v34, v156
	s_mov_b64 s[6:7], 0
	v_mov_b32_e32 v44, 0x3727c5ac
	v_cndmask_b32_e32 v34, v155, v34, vcc
	v_lshlrev_b32_e32 v39, 2, v34
	v_xor_b32_e32 v34, 4, v155
	v_cmp_lt_i32_e32 vcc, v34, v156
	s_mov_b32 s8, 0x800000
	s_mov_b32 s9, 0x83ff
	v_cndmask_b32_e32 v34, v155, v34, vcc
	v_lshlrev_b32_e32 v40, 2, v34
	v_xor_b32_e32 v34, 8, v155
	v_cmp_lt_i32_e32 vcc, v34, v156
	s_nop 1
	v_cndmask_b32_e32 v34, v155, v34, vcc
	v_cmp_lt_i32_e32 vcc, v157, v156
	v_lshlrev_b32_e32 v41, 2, v34
	s_nop 0
	v_cndmask_b32_e32 v34, v155, v157, vcc
	v_cmp_lt_i32_e32 vcc, v158, v156
	v_lshlrev_b32_e32 v42, 2, v34
	s_nop 0
	v_cndmask_b32_e32 v34, v155, v158, vcc
	v_lshlrev_b32_e32 v43, 2, v34
	v_lshlrev_b32_e32 v34, 3, v33
	v_lshl_add_u64 v[36:37], s[0:1], 0, v[34:35]
	s_mov_b64 s[0:1], 0xc8c4000
	v_lshl_add_u64 v[34:35], v[36:37], 0, s[0:1]
	s_mov_b64 s[0:1], 0x86c4000
	v_lshl_add_u64 v[36:37], v[36:37], 0, s[0:1]
	v_readfirstlane_b32 s98, v32
	s_nop 3
	s_lshl_b32 s99, s84, 3
	s_lshl_b32 s100, s98, 11
	s_mov_b32 s101, 0
	v_lshl_add_u64 v[32:33], v[34:35], 0, s[100:101]
	global_load_dwordx2 v[38:39], v[32:33], off
	global_load_dwordx2 v[40:41], v[32:33], off offset:512
	global_load_dwordx2 v[42:43], v[32:33], off offset:1024
	global_load_dwordx2 v[44:45], v[32:33], off offset:1536
	s_add_i32 s100, s98, s99
	s_cmp_ge_i32 s100, 0x8400
	s_cbranch_scc1 .Lln1_p0
	s_lshl_b32 s100, s100, 11
	v_lshl_add_u64 v[32:33], v[34:35], 0, s[100:101]
	global_load_dwordx2 v[46:47], v[32:33], off
	global_load_dwordx2 v[48:49], v[32:33], off offset:512
	global_load_dwordx2 v[50:51], v[32:33], off offset:1024
	global_load_dwordx2 v[52:53], v[32:33], off offset:1536
	s_waitcnt vmcnt(4)
	s_branch .Lln1_A_go
.Lln1_p0:
	s_waitcnt vmcnt(0)
	s_branch .Lln1_A_go
.Lln1_A:
	s_add_i32 s100, s98, s99
	s_cmp_ge_i32 s100, 0x8400
	s_cbranch_scc1 .Lln1_A_w4
	s_waitcnt vmcnt(8)
	s_branch .Lln1_A_go
.Lln1_A_w4:
	s_waitcnt vmcnt(4)
.Lln1_A_go:
	v_lshlrev_b32_e32 v54, 16, v38
	v_and_b32_e32 v55, 0xffff0000, v38
	v_lshlrev_b32_e32 v56, 16, v39
	v_and_b32_e32 v57, 0xffff0000, v39
	v_lshlrev_b32_e32 v58, 16, v40
	v_and_b32_e32 v59, 0xffff0000, v40
	v_lshlrev_b32_e32 v60, 16, v41
	v_and_b32_e32 v61, 0xffff0000, v41
	v_lshlrev_b32_e32 v62, 16, v42
	v_and_b32_e32 v63, 0xffff0000, v42
	v_lshlrev_b32_e32 v64, 16, v43
	v_and_b32_e32 v65, 0xffff0000, v43
	v_lshlrev_b32_e32 v66, 16, v44
	v_and_b32_e32 v67, 0xffff0000, v44
	v_lshlrev_b32_e32 v68, 16, v45
	v_and_b32_e32 v69, 0xffff0000, v45
	s_lshl_b32 s100, s98, 11
	s_mov_b32 s101, 0
	v_lshl_add_u64 v[38:39], v[36:37], 0, s[100:101]
	v_pk_add_f32 v[40:41], v[54:55], v[56:57]
	v_pk_add_f32 v[42:43], v[58:59], v[60:61]
	v_pk_add_f32 v[44:45], v[62:63], v[64:65]
	v_pk_add_f32 v[32:33], v[66:67], v[68:69]
	v_pk_add_f32 v[40:41], v[40:41], v[42:43]
	v_pk_add_f32 v[44:45], v[44:45], v[32:33]
	s_nop 0
	v_pk_add_f32 v[40:41], v[40:41], v[44:45]
	s_nop 0
	v_add_f32_e32 v32, v40, v41
	s_nop 1
	v_add_f32_dpp v33, v32, v32 quad_perm:[1,0,3,2] row_mask:0xf bank_mask:0xf
	s_nop 1
	v_add_f32_dpp v32, v33, v33 quad_perm:[2,3,0,1] row_mask:0xf bank_mask:0xf
	s_nop 1
	v_add_f32_dpp v33, v32, v32 row_half_mirror row_mask:0xf bank_mask:0xf
	s_nop 1
	v_add_f32_dpp v32, v33, v33 row_mirror row_mask:0xf bank_mask:0xf
	s_nop 0
	v_readlane_b32 s100, v32, 0
	v_readlane_b32 s101, v32, 16
	s_nop 1
	v_mov_b32_e32 v33, s100
	v_add_f32_e32 v33, s101, v33
	v_readlane_b32 s100, v32, 32
	v_readlane_b32 s101, v32, 48
	s_nop 1
	v_add_f32_e32 v33, s100, v33
	v_add_f32_e32 v32, s101, v33
	v_mul_f32_e32 v32, 0x3a800000, v32
	v_pk_add_f32 v[54:55], v[54:55], v[32:33] op_sel_hi:[1,0] neg_lo:[0,1] neg_hi:[0,1]
	v_pk_add_f32 v[56:57], v[56:57], v[32:33] op_sel_hi:[1,0] neg_lo:[0,1] neg_hi:[0,1]
	v_pk_add_f32 v[58:59], v[58:59], v[32:33] op_sel_hi:[1,0] neg_lo:[0,1] neg_hi:[0,1]
	v_pk_add_f32 v[60:61], v[60:61], v[32:33] op_sel_hi:[1,0] neg_lo:[0,1] neg_hi:[0,1]
	v_pk_add_f32 v[62:63], v[62:63], v[32:33] op_sel_hi:[1,0] neg_lo:[0,1] neg_hi:[0,1]
	v_pk_add_f32 v[64:65], v[64:65], v[32:33] op_sel_hi:[1,0] neg_lo:[0,1] neg_hi:[0,1]
	v_pk_add_f32 v[66:67], v[66:67], v[32:33] op_sel_hi:[1,0] neg_lo:[0,1] neg_hi:[0,1]
	v_pk_add_f32 v[68:69], v[68:69], v[32:33] op_sel_hi:[1,0] neg_lo:[0,1] neg_hi:[0,1]
	v_pk_mul_f32 v[40:41], v[54:55], v[54:55]
	v_pk_mul_f32 v[42:43], v[56:57], v[56:57]
	v_pk_mul_f32 v[44:45], v[58:59], v[58:59]
	v_pk_fma_f32 v[40:41], v[60:61], v[60:61], v[40:41]
	v_pk_fma_f32 v[42:43], v[62:63], v[62:63], v[42:43]
	v_pk_fma_f32 v[44:45], v[64:65], v[64:65], v[44:45]
	v_pk_fma_f32 v[40:41], v[66:67], v[66:67], v[40:41]
	v_pk_fma_f32 v[42:43], v[68:69], v[68:69], v[42:43]
	v_pk_add_f32 v[40:41], v[40:41], v[44:45]
	s_nop 0
	v_pk_add_f32 v[40:41], v[40:41], v[42:43]
	s_nop 0
	v_add_f32_e32 v32, v40, v41
	s_nop 1
	v_add_f32_dpp v33, v32, v32 quad_perm:[1,0,3,2] row_mask:0xf bank_mask:0xf
	s_nop 1
	v_add_f32_dpp v32, v33, v33 quad_perm:[2,3,0,1] row_mask:0xf bank_mask:0xf
	s_nop 1
	v_add_f32_dpp v33, v32, v32 row_half_mirror row_mask:0xf bank_mask:0xf
	s_nop 1
	v_add_f32_dpp v32, v33, v33 row_mirror row_mask:0xf bank_mask:0xf
	s_nop 0
	v_readlane_b32 s100, v32, 0
	v_readlane_b32 s101, v32, 16
	s_nop 1
	v_mov_b32_e32 v33, s100
	v_add_f32_e32 v33, s101, v33
	v_readlane_b32 s100, v32, 32
	v_readlane_b32 s101, v32, 48
	s_nop 1
	v_add_f32_e32 v33, s100, v33
	v_add_f32_e32 v32, s101, v33
	v_mul_f32_e32 v32, 0x3a800000, v32
	v_add_f32_e32 v32, 0x3727c5ac, v32
	v_rsq_f32_e32 v32, v32
	s_nop 0
	v_pk_mul_f32 v[54:55], v[54:55], v[32:33] op_sel_hi:[1,0]
	v_pk_mul_f32 v[56:57], v[56:57], v[32:33] op_sel_hi:[1,0]
	v_pk_mul_f32 v[58:59], v[58:59], v[32:33] op_sel_hi:[1,0]
	v_pk_mul_f32 v[60:61], v[60:61], v[32:33] op_sel_hi:[1,0]
	v_pk_mul_f32 v[62:63], v[62:63], v[32:33] op_sel_hi:[1,0]
	v_pk_mul_f32 v[64:65], v[64:65], v[32:33] op_sel_hi:[1,0]
	v_pk_mul_f32 v[66:67], v[66:67], v[32:33] op_sel_hi:[1,0]
	v_pk_mul_f32 v[68:69], v[68:69], v[32:33] op_sel_hi:[1,0]
	v_pk_fma_f32 v[54:55], v[0:1], v[54:55], v[4:5]
	v_pk_fma_f32 v[56:57], v[2:3], v[56:57], v[6:7]
	v_pk_fma_f32 v[58:59], v[8:9], v[58:59], v[12:13]
	v_pk_fma_f32 v[60:61], v[10:11], v[60:61], v[14:15]
	v_pk_fma_f32 v[62:63], v[16:17], v[62:63], v[20:21]
	v_pk_fma_f32 v[64:65], v[18:19], v[64:65], v[22:23]
	v_pk_fma_f32 v[66:67], v[24:25], v[66:67], v[28:29]
	v_pk_fma_f32 v[68:69], v[26:27], v[68:69], v[30:31]
	v_cvt_pk_bf16_f32 v54, v54, v55
	v_cvt_pk_bf16_f32 v55, v56, v57
	v_cvt_pk_bf16_f32 v56, v58, v59
	v_cvt_pk_bf16_f32 v57, v60, v61
	v_cvt_pk_bf16_f32 v58, v62, v63
	v_cvt_pk_bf16_f32 v59, v64, v65
	v_cvt_pk_bf16_f32 v60, v66, v67
	v_cvt_pk_bf16_f32 v61, v68, v69
	global_store_dwordx2 v[38:39], v[54:55], off
	global_store_dwordx2 v[38:39], v[56:57], off offset:512
	global_store_dwordx2 v[38:39], v[58:59], off offset:1024
	global_store_dwordx2 v[38:39], v[60:61], off offset:1536
	s_lshl_b32 s100, s99, 1
	s_add_i32 s100, s100, s98
	s_cmp_ge_i32 s100, 0x8400
	s_cbranch_scc1 .Lln1_A_nopf
	s_lshl_b32 s100, s100, 11
	s_mov_b32 s101, 0
	v_lshl_add_u64 v[32:33], v[34:35], 0, s[100:101]
	global_load_dwordx2 v[38:39], v[32:33], off
	global_load_dwordx2 v[40:41], v[32:33], off offset:512
	global_load_dwordx2 v[42:43], v[32:33], off offset:1024
	global_load_dwordx2 v[44:45], v[32:33], off offset:1536
.Lln1_A_nopf:
	s_add_i32 s98, s98, s99
	s_cmp_ge_i32 s98, 0x8400
	s_cbranch_scc1 .Lln1_done

.Lln1_B_go:
	v_lshlrev_b32_e32 v54, 16, v46
	v_and_b32_e32 v55, 0xffff0000, v46
	v_lshlrev_b32_e32 v56, 16, v47
	v_and_b32_e32 v57, 0xffff0000, v47
	v_lshlrev_b32_e32 v58, 16, v48
	v_and_b32_e32 v59, 0xffff0000, v48
	v_lshlrev_b32_e32 v60, 16, v49
	v_and_b32_e32 v61, 0xffff0000, v49
	v_lshlrev_b32_e32 v62, 16, v50
	v_and_b32_e32 v63, 0xffff0000, v50
	v_lshlrev_b32_e32 v64, 16, v51
	v_and_b32_e32 v65, 0xffff0000, v51
	v_lshlrev_b32_e32 v66, 16, v52
	v_and_b32_e32 v67, 0xffff0000, v52
	v_lshlrev_b32_e32 v68, 16, v53
	v_and_b32_e32 v69, 0xffff0000, v53
	s_lshl_b32 s100, s98, 11
	s_mov_b32 s101, 0
	v_lshl_add_u64 v[46:47], v[36:37], 0, s[100:101]
	v_pk_add_f32 v[48:49], v[54:55], v[56:57]
	v_pk_add_f32 v[50:51], v[58:59], v[60:61]
	v_pk_add_f32 v[52:53], v[62:63], v[64:65]
	v_pk_add_f32 v[32:33], v[66:67], v[68:69]
	v_pk_add_f32 v[48:49], v[48:49], v[50:51]
	v_pk_add_f32 v[52:53], v[52:53], v[32:33]
	s_nop 0
	v_pk_add_f32 v[48:49], v[48:49], v[52:53]
	s_nop 0
	v_add_f32_e32 v32, v48, v49
	s_nop 1
	v_add_f32_dpp v33, v32, v32 quad_perm:[1,0,3,2] row_mask:0xf bank_mask:0xf
	s_nop 1
	v_add_f32_dpp v32, v33, v33 quad_perm:[2,3,0,1] row_mask:0xf bank_mask:0xf
	s_nop 1
	v_add_f32_dpp v33, v32, v32 row_half_mirror row_mask:0xf bank_mask:0xf
	s_nop 1
	v_add_f32_dpp v32, v33, v33 row_mirror row_mask:0xf bank_mask:0xf
	s_nop 0
	v_readlane_b32 s100, v32, 0
	v_readlane_b32 s101, v32, 16
	s_nop 1
	v_mov_b32_e32 v33, s100
	v_add_f32_e32 v33, s101, v33
	v_readlane_b32 s100, v32, 32
	v_readlane_b32 s101, v32, 48
	s_nop 1
	v_add_f32_e32 v33, s100, v33
	v_add_f32_e32 v32, s101, v33
	v_mul_f32_e32 v32, 0x3a800000, v32
	v_pk_add_f32 v[54:55], v[54:55], v[32:33] op_sel_hi:[1,0] neg_lo:[0,1] neg_hi:[0,1]
	v_pk_add_f32 v[56:57], v[56:57], v[32:33] op_sel_hi:[1,0] neg_lo:[0,1] neg_hi:[0,1]
	v_pk_add_f32 v[58:59], v[58:59], v[32:33] op_sel_hi:[1,0] neg_lo:[0,1] neg_hi:[0,1]
	v_pk_add_f32 v[60:61], v[60:61], v[32:33] op_sel_hi:[1,0] neg_lo:[0,1] neg_hi:[0,1]
	v_pk_add_f32 v[62:63], v[62:63], v[32:33] op_sel_hi:[1,0] neg_lo:[0,1] neg_hi:[0,1]
	v_pk_add_f32 v[64:65], v[64:65], v[32:33] op_sel_hi:[1,0] neg_lo:[0,1] neg_hi:[0,1]
	v_pk_add_f32 v[66:67], v[66:67], v[32:33] op_sel_hi:[1,0] neg_lo:[0,1] neg_hi:[0,1]
	v_pk_add_f32 v[68:69], v[68:69], v[32:33] op_sel_hi:[1,0] neg_lo:[0,1] neg_hi:[0,1]
	v_pk_mul_f32 v[48:49], v[54:55], v[54:55]
	v_pk_mul_f32 v[50:51], v[56:57], v[56:57]
	v_pk_mul_f32 v[52:53], v[58:59], v[58:59]
	v_pk_fma_f32 v[48:49], v[60:61], v[60:61], v[48:49]
	v_pk_fma_f32 v[50:51], v[62:63], v[62:63], v[50:51]
	v_pk_fma_f32 v[52:53], v[64:65], v[64:65], v[52:53]
	v_pk_fma_f32 v[48:49], v[66:67], v[66:67], v[48:49]
	v_pk_fma_f32 v[50:51], v[68:69], v[68:69], v[50:51]
	v_pk_add_f32 v[48:49], v[48:49], v[52:53]
	s_nop 0
	v_pk_add_f32 v[48:49], v[48:49], v[50:51]
	s_nop 0
	v_add_f32_e32 v32, v48, v49
	s_nop 1
	v_add_f32_dpp v33, v32, v32 quad_perm:[1,0,3,2] row_mask:0xf bank_mask:0xf
	s_nop 1
	v_add_f32_dpp v32, v33, v33 quad_perm:[2,3,0,1] row_mask:0xf bank_mask:0xf
	s_nop 1
	v_add_f32_dpp v33, v32, v32 row_half_mirror row_mask:0xf bank_mask:0xf
	s_nop 1
	v_add_f32_dpp v32, v33, v33 row_mirror row_mask:0xf bank_mask:0xf
	s_nop 0
	v_readlane_b32 s100, v32, 0
	v_readlane_b32 s101, v32, 16
	s_nop 1
	v_mov_b32_e32 v33, s100
	v_add_f32_e32 v33, s101, v33
	v_readlane_b32 s100, v32, 32
	v_readlane_b32 s101, v32, 48
	s_nop 1
	v_add_f32_e32 v33, s100, v33
	v_add_f32_e32 v32, s101, v33
	v_mul_f32_e32 v32, 0x3a800000, v32
	v_add_f32_e32 v32, 0x3727c5ac, v32
	v_rsq_f32_e32 v32, v32
	s_nop 0
	v_pk_mul_f32 v[54:55], v[54:55], v[32:33] op_sel_hi:[1,0]
	v_pk_mul_f32 v[56:57], v[56:57], v[32:33] op_sel_hi:[1,0]
	v_pk_mul_f32 v[58:59], v[58:59], v[32:33] op_sel_hi:[1,0]
	v_pk_mul_f32 v[60:61], v[60:61], v[32:33] op_sel_hi:[1,0]
	v_pk_mul_f32 v[62:63], v[62:63], v[32:33] op_sel_hi:[1,0]
	v_pk_mul_f32 v[64:65], v[64:65], v[32:33] op_sel_hi:[1,0]
	v_pk_mul_f32 v[66:67], v[66:67], v[32:33] op_sel_hi:[1,0]
	v_pk_mul_f32 v[68:69], v[68:69], v[32:33] op_sel_hi:[1,0]
	v_pk_fma_f32 v[54:55], v[0:1], v[54:55], v[4:5]
	v_pk_fma_f32 v[56:57], v[2:3], v[56:57], v[6:7]
	v_pk_fma_f32 v[58:59], v[8:9], v[58:59], v[12:13]
	v_pk_fma_f32 v[60:61], v[10:11], v[60:61], v[14:15]
	v_pk_fma_f32 v[62:63], v[16:17], v[62:63], v[20:21]
	v_pk_fma_f32 v[64:65], v[18:19], v[64:65], v[22:23]
	v_pk_fma_f32 v[66:67], v[24:25], v[66:67], v[28:29]
	v_pk_fma_f32 v[68:69], v[26:27], v[68:69], v[30:31]
	v_cvt_pk_bf16_f32 v54, v54, v55
	v_cvt_pk_bf16_f32 v55, v56, v57
	v_cvt_pk_bf16_f32 v56, v58, v59
	v_cvt_pk_bf16_f32 v57, v60, v61
	v_cvt_pk_bf16_f32 v58, v62, v63
	v_cvt_pk_bf16_f32 v59, v64, v65
	v_cvt_pk_bf16_f32 v60, v66, v67
	v_cvt_pk_bf16_f32 v61, v68, v69
	global_store_dwordx2 v[46:47], v[54:55], off
	global_store_dwordx2 v[46:47], v[56:57], off offset:512
	global_store_dwordx2 v[46:47], v[58:59], off offset:1024
	global_store_dwordx2 v[46:47], v[60:61], off offset:1536
	s_lshl_b32 s100, s99, 1
	s_add_i32 s100, s100, s98
	s_cmp_ge_i32 s100, 0x8400
	s_cbranch_scc1 .Lln1_B_nopf
	s_lshl_b32 s100, s100, 11
	s_mov_b32 s101, 0
	v_lshl_add_u64 v[32:33], v[34:35], 0, s[100:101]
	global_load_dwordx2 v[46:47], v[32:33], off
	global_load_dwordx2 v[48:49], v[32:33], off offset:512
	global_load_dwordx2 v[50:51], v[32:33], off offset:1024
	global_load_dwordx2 v[52:53], v[32:33], off offset:1536
.Lln1_B_nopf:
	s_add_i32 s98, s98, s99
	s_cmp_ge_i32 s98, 0x8400
	s_cbranch_scc1 .Lln1_done
	s_branch .Lln1_A
.Lln1_done:
.LBB0_632:
	s_or_b64 exec, exec, s[4:5]
	s_getreg_b32 s2, hwreg(HW_REG_XCC_ID, 0, 4)
	s_waitcnt vmcnt(0)
	s_waitcnt vmcnt(0)
	v_mov_b32_e32 v0, v154
	s_waitcnt lgkmcnt(0)
	s_barrier
	s_nop 0
	v_cmp_eq_u32_e32 vcc, 0, v0
	s_and_saveexec_b64 s[0:1], vcc
	s_cbranch_execz .LBB0_684
	s_add_i32 s4, 0, 0x20010
	v_mov_b32_e32 v0, s4
	s_waitcnt vmcnt(0) expcnt(0) lgkmcnt(0)
	ds_read_b32 v2, v0
	s_add_i32 s4, 0, 0x20014
	v_mov_b32_e32 v0, s4
	ds_read_b32 v0, v0
	s_and_b32 s2, s2, 15
	s_waitcnt lgkmcnt(1)
	v_cmp_ne_u32_e32 vcc, 0, v2
	s_cbranch_vccnz .LBB0_648
	v_readlane_b32 s4, v255, 1
	s_mul_i32 s18, s85, s4
	s_add_u32 s4, s36, 0x1000
	s_addc_u32 s5, s37, 0
	s_add_u32 s6, s36, 0x1100
	s_addc_u32 s7, s37, 0
	s_add_u32 s8, s36, 0x1200
	s_addc_u32 s9, s37, 0
	s_add_u32 s10, s36, 0x1300
	s_mul_i32 s18, s18, s84
	s_addc_u32 s11, s37, 0
	s_mov_b32 s19, 1
	v_mov_b32_e32 v16, 0
	s_branch .LBB0_636

.LBB0_810:
	s_or_b64 exec, exec, s[0:1]
	s_mov_b64 s[0:1], s[36:37]
	s_mov_b64 s[4:5], s[94:95]
	s_waitcnt lgkmcnt(0)
	s_barrier
	v_mov_b32_e32 v0, v154
	v_readlane_b32 s4, v255, 20
	v_and_b32_e32 v33, 63, v0
	v_mov_b32_e32 v32, v154
	v_lshlrev_b32_e32 v34, 4, v33
	v_readlane_b32 s18, v255, 34
	v_readlane_b32 s19, v255, 35
	s_nop 4
	global_load_dwordx4 v[0:3], v34, s[18:19]
	global_load_dwordx4 v[4:7], v34, s[18:19] offset:1024
	global_load_dwordx4 v[8:11], v34, s[92:93]
	global_load_dwordx4 v[12:15], v34, s[92:93] offset:1024
	global_load_dwordx4 v[16:19], v34, s[18:19] offset:2048
	global_load_dwordx4 v[20:23], v34, s[18:19] offset:3072
	global_load_dwordx4 v[24:27], v34, s[92:93] offset:2048
	global_load_dwordx4 v[28:31], v34, s[92:93] offset:3072
	v_readlane_b32 s2, v255, 0
	v_ashrrev_i32_e32 v32, 6, v32
	v_readlane_b32 s5, v255, 21
	v_lshl_add_u32 v32, s2, 3, v32
	s_mov_b32 s2, 0x8400
	v_cmp_gt_i32_e32 vcc, s2, v32
	v_readlane_b32 s6, v255, 22
	v_readlane_b32 s7, v255, 23
	v_readlane_b32 s8, v255, 24
	v_readlane_b32 s9, v255, 25
	v_readlane_b32 s10, v255, 26
	v_readlane_b32 s11, v255, 27
	v_readlane_b32 s12, v255, 28
	v_readlane_b32 s13, v255, 29
	v_readlane_b32 s14, v255, 30
	v_readlane_b32 s15, v255, 31
	v_readlane_b32 s16, v255, 32
	v_readlane_b32 s17, v255, 33
	s_and_saveexec_b64 s[4:5], vcc
	s_cbranch_execz .LBB0_813
	v_xor_b32_e32 v34, 1, v155
	v_cmp_lt_i32_e32 vcc, v34, v156
	v_mov_b32_e32 v35, 0
	s_lshl_b32 s2, s84, 3
	v_cndmask_b32_e32 v34, v155, v34, vcc
	v_lshlrev_b32_e32 v36, 2, v34
	v_xor_b32_e32 v34, 2, v155
	v_cmp_lt_i32_e32 vcc, v34, v156
	s_mov_b64 s[6:7], 0
	v_mov_b32_e32 v42, 0x3727c5ac
	v_cndmask_b32_e32 v34, v155, v34, vcc
	v_lshlrev_b32_e32 v37, 2, v34
	v_xor_b32_e32 v34, 4, v155
	v_cmp_lt_i32_e32 vcc, v34, v156
	s_mov_b32 s8, 0x800000
	s_mov_b32 s9, 0x83ff
	v_cndmask_b32_e32 v34, v155, v34, vcc
	v_lshlrev_b32_e32 v38, 2, v34
	v_xor_b32_e32 v34, 8, v155
	v_cmp_lt_i32_e32 vcc, v34, v156
	s_nop 1
	v_cndmask_b32_e32 v34, v155, v34, vcc
	v_cmp_lt_i32_e32 vcc, v157, v156
	v_lshlrev_b32_e32 v39, 2, v34
	s_nop 0
	v_cndmask_b32_e32 v34, v155, v157, vcc
	v_cmp_lt_i32_e32 vcc, v158, v156
	v_lshlrev_b32_e32 v40, 2, v34
	s_nop 0
	v_cndmask_b32_e32 v34, v155, v158, vcc
	v_lshlrev_b32_e32 v41, 2, v34
	v_lshlrev_b32_e32 v34, 3, v33
	v_lshl_add_u64 v[34:35], s[0:1], 0, v[34:35]
	s_mov_b64 s[0:1], 0x44c4000
	v_lshl_add_u64 v[34:35], v[34:35], 0, s[0:1]
	v_readfirstlane_b32 s98, v32
	s_nop 3
	s_lshl_b32 s99, s84, 3
	s_lshl_b32 s100, s98, 11
	s_mov_b32 s101, 0
	v_lshl_add_u64 v[32:33], v[34:35], 0, s[100:101]
	global_load_dwordx2 v[38:39], v[32:33], off
	global_load_dwordx2 v[40:41], v[32:33], off offset:512
	global_load_dwordx2 v[42:43], v[32:33], off offset:1024
	global_load_dwordx2 v[44:45], v[32:33], off offset:1536
	s_add_i32 s100, s98, s99
	s_cmp_ge_i32 s100, 0x8400
	s_cbranch_scc1 .Lln2_p0
	s_lshl_b32 s100, s100, 11
	v_lshl_add_u64 v[32:33], v[34:35], 0, s[100:101]
	global_load_dwordx2 v[46:47], v[32:33], off
	global_load_dwordx2 v[48:49], v[32:33], off offset:512
	global_load_dwordx2 v[50:51], v[32:33], off offset:1024
	global_load_dwordx2 v[52:53], v[32:33], off offset:1536
	s_waitcnt vmcnt(4)
	s_branch .Lln2_A_go

.Lln2_A_go:
	v_lshlrev_b32_e32 v54, 16, v38
	v_and_b32_e32 v55, 0xffff0000, v38
	v_lshlrev_b32_e32 v56, 16, v39
	v_and_b32_e32 v57, 0xffff0000, v39
	v_lshlrev_b32_e32 v58, 16, v40
	v_and_b32_e32 v59, 0xffff0000, v40
	v_lshlrev_b32_e32 v60, 16, v41
	v_and_b32_e32 v61, 0xffff0000, v41
	v_lshlrev_b32_e32 v62, 16, v42
	v_and_b32_e32 v63, 0xffff0000, v42
	v_lshlrev_b32_e32 v64, 16, v43
	v_and_b32_e32 v65, 0xffff0000, v43
	v_lshlrev_b32_e32 v66, 16, v44
	v_and_b32_e32 v67, 0xffff0000, v44
	v_lshlrev_b32_e32 v68, 16, v45
	v_and_b32_e32 v69, 0xffff0000, v45
	s_lshl_b32 s100, s98, 11
	s_mov_b32 s101, 0
	v_lshl_add_u64 v[38:39], v[34:35], 0, s[100:101]
	v_pk_add_f32 v[40:41], v[54:55], v[56:57]
	v_pk_add_f32 v[42:43], v[58:59], v[60:61]
	v_pk_add_f32 v[44:45], v[62:63], v[64:65]
	v_pk_add_f32 v[32:33], v[66:67], v[68:69]
	v_pk_add_f32 v[40:41], v[40:41], v[42:43]
	v_pk_add_f32 v[44:45], v[44:45], v[32:33]
	s_nop 0
	v_pk_add_f32 v[40:41], v[40:41], v[44:45]
	s_nop 0
	v_add_f32_e32 v32, v40, v41
	s_nop 1
	v_add_f32_dpp v33, v32, v32 quad_perm:[1,0,3,2] row_mask:0xf bank_mask:0xf
	s_nop 1
	v_add_f32_dpp v32, v33, v33 quad_perm:[2,3,0,1] row_mask:0xf bank_mask:0xf
	s_nop 1
	v_add_f32_dpp v33, v32, v32 row_half_mirror row_mask:0xf bank_mask:0xf
	s_nop 1
	v_add_f32_dpp v32, v33, v33 row_mirror row_mask:0xf bank_mask:0xf
	s_nop 0
	v_readlane_b32 s100, v32, 0
	v_readlane_b32 s101, v32, 16
	s_nop 1
	v_mov_b32_e32 v33, s100
	v_add_f32_e32 v33, s101, v33
	v_readlane_b32 s100, v32, 32
	v_readlane_b32 s101, v32, 48
	s_nop 1
	v_add_f32_e32 v33, s100, v33
	v_add_f32_e32 v32, s101, v33
	v_mul_f32_e32 v32, 0x3a800000, v32
	v_pk_add_f32 v[54:55], v[54:55], v[32:33] op_sel_hi:[1,0] neg_lo:[0,1] neg_hi:[0,1]
	v_pk_add_f32 v[56:57], v[56:57], v[32:33] op_sel_hi:[1,0] neg_lo:[0,1] neg_hi:[0,1]
	v_pk_add_f32 v[58:59], v[58:59], v[32:33] op_sel_hi:[1,0] neg_lo:[0,1] neg_hi:[0,1]
	v_pk_add_f32 v[60:61], v[60:61], v[32:33] op_sel_hi:[1,0] neg_lo:[0,1] neg_hi:[0,1]
	v_pk_add_f32 v[62:63], v[62:63], v[32:33] op_sel_hi:[1,0] neg_lo:[0,1] neg_hi:[0,1]
	v_pk_add_f32 v[64:65], v[64:65], v[32:33] op_sel_hi:[1,0] neg_lo:[0,1] neg_hi:[0,1]
	v_pk_add_f32 v[66:67], v[66:67], v[32:33] op_sel_hi:[1,0] neg_lo:[0,1] neg_hi:[0,1]
	v_pk_add_f32 v[68:69], v[68:69], v[32:33] op_sel_hi:[1,0] neg_lo:[0,1] neg_hi:[0,1]
	v_pk_mul_f32 v[40:41], v[54:55], v[54:55]
	v_pk_mul_f32 v[42:43], v[56:57], v[56:57]
	v_pk_mul_f32 v[44:45], v[58:59], v[58:59]
	v_pk_fma_f32 v[40:41], v[60:61], v[60:61], v[40:41]
	v_pk_fma_f32 v[42:43], v[62:63], v[62:63], v[42:43]
	v_pk_fma_f32 v[44:45], v[64:65], v[64:65], v[44:45]
	v_pk_fma_f32 v[40:41], v[66:67], v[66:67], v[40:41]
	v_pk_fma_f32 v[42:43], v[68:69], v[68:69], v[42:43]
	v_pk_add_f32 v[40:41], v[40:41], v[44:45]
	s_nop 0
	v_pk_add_f32 v[40:41], v[40:41], v[42:43]
	s_nop 0
	v_add_f32_e32 v32, v40, v41
	s_nop 1
	v_add_f32_dpp v33, v32, v32 quad_perm:[1,0,3,2] row_mask:0xf bank_mask:0xf
	s_nop 1
	v_add_f32_dpp v32, v33, v33 quad_perm:[2,3,0,1] row_mask:0xf bank_mask:0xf
	s_nop 1
	v_add_f32_dpp v33, v32, v32 row_half_mirror row_mask:0xf bank_mask:0xf
	s_nop 1
	v_add_f32_dpp v32, v33, v33 row_mirror row_mask:0xf bank_mask:0xf
	s_nop 0
	v_readlane_b32 s100, v32, 0
	v_readlane_b32 s101, v32, 16
	s_nop 1
	v_mov_b32_e32 v33, s100
	v_add_f32_e32 v33, s101, v33
	v_readlane_b32 s100, v32, 32
	v_readlane_b32 s101, v32, 48
	s_nop 1
	v_add_f32_e32 v33, s100, v33
	v_add_f32_e32 v32, s101, v33
	v_mul_f32_e32 v32, 0x3a800000, v32
	v_add_f32_e32 v32, 0x3727c5ac, v32
	v_rsq_f32_e32 v32, v32
	s_nop 0
	v_pk_mul_f32 v[54:55], v[54:55], v[32:33] op_sel_hi:[1,0]
	v_pk_mul_f32 v[56:57], v[56:57], v[32:33] op_sel_hi:[1,0]
	v_pk_mul_f32 v[58:59], v[58:59], v[32:33] op_sel_hi:[1,0]
	v_pk_mul_f32 v[60:61], v[60:61], v[32:33] op_sel_hi:[1,0]
	v_pk_mul_f32 v[62:63], v[62:63], v[32:33] op_sel_hi:[1,0]
	v_pk_mul_f32 v[64:65], v[64:65], v[32:33] op_sel_hi:[1,0]
	v_pk_mul_f32 v[66:67], v[66:67], v[32:33] op_sel_hi:[1,0]
	v_pk_mul_f32 v[68:69], v[68:69], v[32:33] op_sel_hi:[1,0]
	v_pk_fma_f32 v[54:55], v[0:1], v[54:55], v[8:9]
	v_pk_fma_f32 v[56:57], v[2:3], v[56:57], v[10:11]
	v_pk_fma_f32 v[58:59], v[4:5], v[58:59], v[12:13]
	v_pk_fma_f32 v[60:61], v[6:7], v[60:61], v[14:15]
	v_pk_fma_f32 v[62:63], v[16:17], v[62:63], v[24:25]
	v_pk_fma_f32 v[64:65], v[18:19], v[64:65], v[26:27]
	v_pk_fma_f32 v[66:67], v[20:21], v[66:67], v[28:29]
	v_pk_fma_f32 v[68:69], v[22:23], v[68:69], v[30:31]
	v_cvt_pk_bf16_f32 v54, v54, v55
	v_cvt_pk_bf16_f32 v55, v56, v57
	v_cvt_pk_bf16_f32 v56, v58, v59
	v_cvt_pk_bf16_f32 v57, v60, v61
	v_cvt_pk_bf16_f32 v58, v62, v63
	v_cvt_pk_bf16_f32 v59, v64, v65
	v_cvt_pk_bf16_f32 v60, v66, v67
	v_cvt_pk_bf16_f32 v61, v68, v69
	global_store_dwordx2 v[38:39], v[54:55], off
	global_store_dwordx2 v[38:39], v[56:57], off offset:512
	global_store_dwordx2 v[38:39], v[58:59], off offset:1024
	global_store_dwordx2 v[38:39], v[60:61], off offset:1536
	s_lshl_b32 s100, s99, 1
	s_add_i32 s100, s100, s98
	s_cmp_ge_i32 s100, 0x8400
	s_cbranch_scc1 .Lln2_A_nopf
	s_lshl_b32 s100, s100, 11
	s_mov_b32 s101, 0
	v_lshl_add_u64 v[32:33], v[34:35], 0, s[100:101]
	global_load_dwordx2 v[38:39], v[32:33], off
	global_load_dwordx2 v[40:41], v[32:33], off offset:512
	global_load_dwordx2 v[42:43], v[32:33], off offset:1024
	global_load_dwordx2 v[44:45], v[32:33], off offset:1536

.Lln2_B_go:
	v_lshlrev_b32_e32 v54, 16, v46
	v_and_b32_e32 v55, 0xffff0000, v46
	v_lshlrev_b32_e32 v56, 16, v47
	v_and_b32_e32 v57, 0xffff0000, v47
	v_lshlrev_b32_e32 v58, 16, v48
	v_and_b32_e32 v59, 0xffff0000, v48
	v_lshlrev_b32_e32 v60, 16, v49
	v_and_b32_e32 v61, 0xffff0000, v49
	v_lshlrev_b32_e32 v62, 16, v50
	v_and_b32_e32 v63, 0xffff0000, v50
	v_lshlrev_b32_e32 v64, 16, v51
	v_and_b32_e32 v65, 0xffff0000, v51
	v_lshlrev_b32_e32 v66, 16, v52
	v_and_b32_e32 v67, 0xffff0000, v52
	v_lshlrev_b32_e32 v68, 16, v53
	v_and_b32_e32 v69, 0xffff0000, v53
	s_lshl_b32 s100, s98, 11
	s_mov_b32 s101, 0
	v_lshl_add_u64 v[46:47], v[34:35], 0, s[100:101]
	v_pk_add_f32 v[48:49], v[54:55], v[56:57]
	v_pk_add_f32 v[50:51], v[58:59], v[60:61]
	v_pk_add_f32 v[52:53], v[62:63], v[64:65]
	v_pk_add_f32 v[32:33], v[66:67], v[68:69]
	v_pk_add_f32 v[48:49], v[48:49], v[50:51]
	v_pk_add_f32 v[52:53], v[52:53], v[32:33]
	s_nop 0
	v_pk_add_f32 v[48:49], v[48:49], v[52:53]
	s_nop 0
	v_add_f32_e32 v32, v48, v49
	s_nop 1
	v_add_f32_dpp v33, v32, v32 quad_perm:[1,0,3,2] row_mask:0xf bank_mask:0xf
	s_nop 1
	v_add_f32_dpp v32, v33, v33 quad_perm:[2,3,0,1] row_mask:0xf bank_mask:0xf
	s_nop 1
	v_add_f32_dpp v33, v32, v32 row_half_mirror row_mask:0xf bank_mask:0xf
	s_nop 1
	v_add_f32_dpp v32, v33, v33 row_mirror row_mask:0xf bank_mask:0xf
	s_nop 0
	v_readlane_b32 s100, v32, 0
	v_readlane_b32 s101, v32, 16
	s_nop 1
	v_mov_b32_e32 v33, s100
	v_add_f32_e32 v33, s101, v33
	v_readlane_b32 s100, v32, 32
	v_readlane_b32 s101, v32, 48
	s_nop 1
	v_add_f32_e32 v33, s100, v33
	v_add_f32_e32 v32, s101, v33
	v_mul_f32_e32 v32, 0x3a800000, v32
	v_pk_add_f32 v[54:55], v[54:55], v[32:33] op_sel_hi:[1,0] neg_lo:[0,1] neg_hi:[0,1]
	v_pk_add_f32 v[56:57], v[56:57], v[32:33] op_sel_hi:[1,0] neg_lo:[0,1] neg_hi:[0,1]
	v_pk_add_f32 v[58:59], v[58:59], v[32:33] op_sel_hi:[1,0] neg_lo:[0,1] neg_hi:[0,1]
	v_pk_add_f32 v[60:61], v[60:61], v[32:33] op_sel_hi:[1,0] neg_lo:[0,1] neg_hi:[0,1]
	v_pk_add_f32 v[62:63], v[62:63], v[32:33] op_sel_hi:[1,0] neg_lo:[0,1] neg_hi:[0,1]
	v_pk_add_f32 v[64:65], v[64:65], v[32:33] op_sel_hi:[1,0] neg_lo:[0,1] neg_hi:[0,1]
	v_pk_add_f32 v[66:67], v[66:67], v[32:33] op_sel_hi:[1,0] neg_lo:[0,1] neg_hi:[0,1]
	v_pk_add_f32 v[68:69], v[68:69], v[32:33] op_sel_hi:[1,0] neg_lo:[0,1] neg_hi:[0,1]
	v_pk_mul_f32 v[48:49], v[54:55], v[54:55]
	v_pk_mul_f32 v[50:51], v[56:57], v[56:57]
	v_pk_mul_f32 v[52:53], v[58:59], v[58:59]
	v_pk_fma_f32 v[48:49], v[60:61], v[60:61], v[48:49]
	v_pk_fma_f32 v[50:51], v[62:63], v[62:63], v[50:51]
	v_pk_fma_f32 v[52:53], v[64:65], v[64:65], v[52:53]
	v_pk_fma_f32 v[48:49], v[66:67], v[66:67], v[48:49]
	v_pk_fma_f32 v[50:51], v[68:69], v[68:69], v[50:51]
	v_pk_add_f32 v[48:49], v[48:49], v[52:53]
	s_nop 0
	v_pk_add_f32 v[48:49], v[48:49], v[50:51]
	s_nop 0
	v_add_f32_e32 v32, v48, v49
	s_nop 1
	v_add_f32_dpp v33, v32, v32 quad_perm:[1,0,3,2] row_mask:0xf bank_mask:0xf
	s_nop 1
	v_add_f32_dpp v32, v33, v33 quad_perm:[2,3,0,1] row_mask:0xf bank_mask:0xf
	s_nop 1
	v_add_f32_dpp v33, v32, v32 row_half_mirror row_mask:0xf bank_mask:0xf
	s_nop 1
	v_add_f32_dpp v32, v33, v33 row_mirror row_mask:0xf bank_mask:0xf
	s_nop 0
	v_readlane_b32 s100, v32, 0
	v_readlane_b32 s101, v32, 16
	s_nop 1
	v_mov_b32_e32 v33, s100
	v_add_f32_e32 v33, s101, v33
	v_readlane_b32 s100, v32, 32
	v_readlane_b32 s101, v32, 48
	s_nop 1
	v_add_f32_e32 v33, s100, v33
	v_add_f32_e32 v32, s101, v33
	v_mul_f32_e32 v32, 0x3a800000, v32
	v_add_f32_e32 v32, 0x3727c5ac, v32
	v_rsq_f32_e32 v32, v32
	s_nop 0
	v_pk_mul_f32 v[54:55], v[54:55], v[32:33] op_sel_hi:[1,0]
	v_pk_mul_f32 v[56:57], v[56:57], v[32:33] op_sel_hi:[1,0]
	v_pk_mul_f32 v[58:59], v[58:59], v[32:33] op_sel_hi:[1,0]
	v_pk_mul_f32 v[60:61], v[60:61], v[32:33] op_sel_hi:[1,0]
	v_pk_mul_f32 v[62:63], v[62:63], v[32:33] op_sel_hi:[1,0]
	v_pk_mul_f32 v[64:65], v[64:65], v[32:33] op_sel_hi:[1,0]
	v_pk_mul_f32 v[66:67], v[66:67], v[32:33] op_sel_hi:[1,0]
	v_pk_mul_f32 v[68:69], v[68:69], v[32:33] op_sel_hi:[1,0]
	v_pk_fma_f32 v[54:55], v[0:1], v[54:55], v[8:9]
	v_pk_fma_f32 v[56:57], v[2:3], v[56:57], v[10:11]
	v_pk_fma_f32 v[58:59], v[4:5], v[58:59], v[12:13]
	v_pk_fma_f32 v[60:61], v[6:7], v[60:61], v[14:15]
	v_pk_fma_f32 v[62:63], v[16:17], v[62:63], v[24:25]
	v_pk_fma_f32 v[64:65], v[18:19], v[64:65], v[26:27]
	v_pk_fma_f32 v[66:67], v[20:21], v[66:67], v[28:29]
	v_pk_fma_f32 v[68:69], v[22:23], v[68:69], v[30:31]
	v_cvt_pk_bf16_f32 v54, v54, v55
	v_cvt_pk_bf16_f32 v55, v56, v57
	v_cvt_pk_bf16_f32 v56, v58, v59
	v_cvt_pk_bf16_f32 v57, v60, v61
	v_cvt_pk_bf16_f32 v58, v62, v63
	v_cvt_pk_bf16_f32 v59, v64, v65
	v_cvt_pk_bf16_f32 v60, v66, v67
	v_cvt_pk_bf16_f32 v61, v68, v69
	global_store_dwordx2 v[46:47], v[54:55], off
	global_store_dwordx2 v[46:47], v[56:57], off offset:512
	global_store_dwordx2 v[46:47], v[58:59], off offset:1024
	global_store_dwordx2 v[46:47], v[60:61], off offset:1536
	s_lshl_b32 s100, s99, 1
	s_add_i32 s100, s100, s98
	s_cmp_ge_i32 s100, 0x8400
	s_cbranch_scc1 .Lln2_B_nopf
	s_lshl_b32 s100, s100, 11
	s_mov_b32 s101, 0
	v_lshl_add_u64 v[32:33], v[34:35], 0, s[100:101]
	global_load_dwordx2 v[46:47], v[32:33], off
	global_load_dwordx2 v[48:49], v[32:33], off offset:512
	global_load_dwordx2 v[50:51], v[32:33], off offset:1024
	global_load_dwordx2 v[52:53], v[32:33], off offset:1536

.LBB0_1743:
	s_or_b64 exec, exec, s[0:1]
	s_mov_b64 s[0:1], s[36:37]
	s_mov_b64 s[4:5], s[94:95]
	s_waitcnt lgkmcnt(0)
	s_barrier
	v_mov_b32_e32 v0, v154
	s_add_u32 s4, s68, 0x1000
	s_addc_u32 s5, s69, 0
	v_and_b32_e32 v33, 63, v0
	v_lshlrev_b32_e32 v24, 4, v33
	s_add_u32 s6, s70, 0x1000
	v_mov_b32_e32 v32, v154
	v_or_b32_e32 v16, 0x400, v24
	v_or_b32_e32 v25, 0x800, v24
	v_or_b32_e32 v34, 0xc00, v24
	s_addc_u32 s7, s71, 0
	global_load_dwordx4 v[0:3], v24, s[4:5]
	global_load_dwordx4 v[4:7], v24, s[6:7]
	global_load_dwordx4 v[8:11], v16, s[4:5]
	global_load_dwordx4 v[12:15], v16, s[6:7]
	s_nop 0
	global_load_dwordx4 v[16:19], v25, s[4:5]
	global_load_dwordx4 v[20:23], v25, s[6:7]
	s_nop 0
	global_load_dwordx4 v[24:27], v34, s[4:5]
	global_load_dwordx4 v[28:31], v34, s[6:7]
	v_readlane_b32 s2, v255, 0
	v_ashrrev_i32_e32 v32, 6, v32
	s_nop 0
	v_lshl_add_u32 v32, s2, 3, v32
	s_mov_b32 s2, 0x8400
	v_cmp_gt_i32_e32 vcc, s2, v32
	s_and_saveexec_b64 s[4:5], vcc
	s_cbranch_execz .LBB0_1746
	v_mov_b32_e32 v35, 0
	v_lshlrev_b32_e32 v34, 3, v33
	v_lshl_add_u64 v[36:37], s[0:1], 0, v[34:35]
	s_mov_b64 s[0:1], 0xc8c4000
	v_lshl_add_u64 v[34:35], v[36:37], 0, s[0:1]
	s_mov_b64 s[0:1], 0x86c4000
	s_lshl_b32 s2, s84, 3
	v_lshl_add_u64 v[36:37], v[36:37], 0, s[0:1]
	s_mov_b64 s[6:7], 0
	v_mov_b32_e32 v38, 0x3727c5ac
	s_mov_b32 s8, 0x800000
	s_mov_b32 s9, 0x83ff
	v_readfirstlane_b32 s98, v32
	s_nop 3
	s_lshl_b32 s99, s84, 3
	s_lshl_b32 s100, s98, 11
	s_mov_b32 s101, 0
	v_lshl_add_u64 v[32:33], v[34:35], 0, s[100:101]
	global_load_dwordx2 v[38:39], v[32:33], off
	global_load_dwordx2 v[40:41], v[32:33], off offset:512
	global_load_dwordx2 v[42:43], v[32:33], off offset:1024
	global_load_dwordx2 v[44:45], v[32:33], off offset:1536
	s_add_i32 s100, s98, s99
	s_cmp_ge_i32 s100, 0x8400
	s_cbranch_scc1 .Lln3_p0
	s_lshl_b32 s100, s100, 11
	v_lshl_add_u64 v[32:33], v[34:35], 0, s[100:101]
	global_load_dwordx2 v[46:47], v[32:33], off
	global_load_dwordx2 v[48:49], v[32:33], off offset:512
	global_load_dwordx2 v[50:51], v[32:33], off offset:1024
	global_load_dwordx2 v[52:53], v[32:33], off offset:1536
	s_waitcnt vmcnt(4)
	s_branch .Lln3_A_go

.LBB0_1924:
	s_or_b64 exec, exec, s[0:1]
	s_waitcnt lgkmcnt(0)
	v_mov_b32_e32 v0, v154
	s_barrier
	s_add_u32 s0, s78, 0x1000
	s_addc_u32 s1, s79, 0
	v_and_b32_e32 v33, 63, v0
	v_lshlrev_b32_e32 v36, 4, v33
	s_add_u32 s2, s92, 0x1000
	v_or_b32_e32 v16, 0x400, v36
	v_or_b32_e32 v24, 0x800, v36
	v_or_b32_e32 v32, 0xc00, v36
	s_addc_u32 s3, s93, 0
	global_load_dwordx4 v[0:3], v36, s[0:1]
	global_load_dwordx4 v[4:7], v36, s[2:3]
	global_load_dwordx4 v[8:11], v16, s[0:1]
	global_load_dwordx4 v[12:15], v16, s[2:3]
	s_nop 0
	global_load_dwordx4 v[16:19], v24, s[0:1]
	global_load_dwordx4 v[20:23], v24, s[2:3]
	s_nop 0
	global_load_dwordx4 v[24:27], v32, s[0:1]
	global_load_dwordx4 v[28:31], v32, s[2:3]
	v_readlane_b32 s0, v255, 0
	v_ashrrev_i32_e32 v32, 6, v154
	s_nop 0
	v_lshl_add_u32 v32, s0, 3, v32
	s_mov_b32 s0, 0x8400
	v_cmp_gt_i32_e32 vcc, s0, v32
	s_and_saveexec_b64 s[0:1], vcc
	s_cbranch_execz .LBB0_1927
	v_mov_b32_e32 v39, 0
	v_lshlrev_b32_e32 v38, 3, v33
	v_lshl_add_u64 v[34:35], s[36:37], 0, v[38:39]
	s_mov_b64 s[0:1], 0x44c4000
	v_mov_b32_e32 v37, v39
	s_lshl_b32 s4, s84, 3
	v_lshl_add_u64 v[34:35], v[34:35], 0, s[0:1]
	v_lshl_add_u64 v[36:37], s[94:95], 0, v[36:37]
	s_mov_b64 s[2:3], 0
	v_mov_b32_e32 v38, 0x3727c5ac
	s_mov_b32 s5, 0x800000
	s_mov_b32 s6, 0x83ff
	v_readfirstlane_b32 s98, v32
	s_nop 3
	s_lshl_b32 s99, s84, 3
	s_lshl_b32 s100, s98, 11
	s_mov_b32 s101, 0
	v_lshl_add_u64 v[32:33], v[34:35], 0, s[100:101]
	global_load_dwordx2 v[38:39], v[32:33], off
	global_load_dwordx2 v[40:41], v[32:33], off offset:512
	global_load_dwordx2 v[42:43], v[32:33], off offset:1024
	global_load_dwordx2 v[44:45], v[32:33], off offset:1536
	s_add_i32 s100, s98, s99
	s_cmp_ge_i32 s100, 0x8400
	s_cbranch_scc1 .Lln4_p0
	s_lshl_b32 s100, s100, 11
	v_lshl_add_u64 v[32:33], v[34:35], 0, s[100:101]
	global_load_dwordx2 v[46:47], v[32:33], off
	global_load_dwordx2 v[48:49], v[32:33], off offset:512
	global_load_dwordx2 v[50:51], v[32:33], off offset:1024
	global_load_dwordx2 v[52:53], v[32:33], off offset:1536
	s_waitcnt vmcnt(4)
	s_branch .Lln4_A_go

.Lln4_A_go:
	v_lshlrev_b32_e32 v54, 16, v38
	v_and_b32_e32 v55, 0xffff0000, v38
	v_lshlrev_b32_e32 v56, 16, v39
	v_and_b32_e32 v57, 0xffff0000, v39
	v_lshlrev_b32_e32 v58, 16, v40
	v_and_b32_e32 v59, 0xffff0000, v40
	v_lshlrev_b32_e32 v60, 16, v41
	v_and_b32_e32 v61, 0xffff0000, v41
	v_lshlrev_b32_e32 v62, 16, v42
	v_and_b32_e32 v63, 0xffff0000, v42
	v_lshlrev_b32_e32 v64, 16, v43
	v_and_b32_e32 v65, 0xffff0000, v43
	v_lshlrev_b32_e32 v66, 16, v44
	v_and_b32_e32 v67, 0xffff0000, v44
	v_lshlrev_b32_e32 v68, 16, v45
	v_and_b32_e32 v69, 0xffff0000, v45
	s_lshl_b32 s100, s98, 12
	s_mov_b32 s101, 0
	v_lshl_add_u64 v[38:39], v[36:37], 0, s[100:101]
	v_pk_add_f32 v[40:41], v[54:55], v[56:57]
	v_pk_add_f32 v[42:43], v[58:59], v[60:61]
	v_pk_add_f32 v[44:45], v[62:63], v[64:65]
	v_pk_add_f32 v[32:33], v[66:67], v[68:69]
	v_pk_add_f32 v[40:41], v[40:41], v[42:43]
	v_pk_add_f32 v[44:45], v[44:45], v[32:33]
	s_nop 0
	v_pk_add_f32 v[40:41], v[40:41], v[44:45]
	s_nop 0
	v_add_f32_e32 v32, v40, v41
	s_nop 1
	v_add_f32_dpp v33, v32, v32 quad_perm:[1,0,3,2] row_mask:0xf bank_mask:0xf
	s_nop 1
	v_add_f32_dpp v32, v33, v33 quad_perm:[2,3,0,1] row_mask:0xf bank_mask:0xf
	s_nop 1
	v_add_f32_dpp v33, v32, v32 row_half_mirror row_mask:0xf bank_mask:0xf
	s_nop 1
	v_add_f32_dpp v32, v33, v33 row_mirror row_mask:0xf bank_mask:0xf
	s_nop 0
	v_readlane_b32 s100, v32, 0
	v_readlane_b32 s101, v32, 16
	s_nop 1
	v_mov_b32_e32 v33, s100
	v_add_f32_e32 v33, s101, v33
	v_readlane_b32 s100, v32, 32
	v_readlane_b32 s101, v32, 48
	s_nop 1
	v_add_f32_e32 v33, s100, v33
	v_add_f32_e32 v32, s101, v33
	v_mul_f32_e32 v32, 0x3a800000, v32
	v_pk_add_f32 v[54:55], v[54:55], v[32:33] op_sel_hi:[1,0] neg_lo:[0,1] neg_hi:[0,1]
	v_pk_add_f32 v[56:57], v[56:57], v[32:33] op_sel_hi:[1,0] neg_lo:[0,1] neg_hi:[0,1]
	v_pk_add_f32 v[58:59], v[58:59], v[32:33] op_sel_hi:[1,0] neg_lo:[0,1] neg_hi:[0,1]
	v_pk_add_f32 v[60:61], v[60:61], v[32:33] op_sel_hi:[1,0] neg_lo:[0,1] neg_hi:[0,1]
	v_pk_add_f32 v[62:63], v[62:63], v[32:33] op_sel_hi:[1,0] neg_lo:[0,1] neg_hi:[0,1]
	v_pk_add_f32 v[64:65], v[64:65], v[32:33] op_sel_hi:[1,0] neg_lo:[0,1] neg_hi:[0,1]
	v_pk_add_f32 v[66:67], v[66:67], v[32:33] op_sel_hi:[1,0] neg_lo:[0,1] neg_hi:[0,1]
	v_pk_add_f32 v[68:69], v[68:69], v[32:33] op_sel_hi:[1,0] neg_lo:[0,1] neg_hi:[0,1]
	v_pk_mul_f32 v[40:41], v[54:55], v[54:55]
	v_pk_mul_f32 v[42:43], v[56:57], v[56:57]
	v_pk_mul_f32 v[44:45], v[58:59], v[58:59]
	v_pk_fma_f32 v[40:41], v[60:61], v[60:61], v[40:41]
	v_pk_fma_f32 v[42:43], v[62:63], v[62:63], v[42:43]
	v_pk_fma_f32 v[44:45], v[64:65], v[64:65], v[44:45]
	v_pk_fma_f32 v[40:41], v[66:67], v[66:67], v[40:41]
	v_pk_fma_f32 v[42:43], v[68:69], v[68:69], v[42:43]
	v_pk_add_f32 v[40:41], v[40:41], v[44:45]
	s_nop 0
	v_pk_add_f32 v[40:41], v[40:41], v[42:43]
	s_nop 0
	v_add_f32_e32 v32, v40, v41
	s_nop 1
	v_add_f32_dpp v33, v32, v32 quad_perm:[1,0,3,2] row_mask:0xf bank_mask:0xf
	s_nop 1
	v_add_f32_dpp v32, v33, v33 quad_perm:[2,3,0,1] row_mask:0xf bank_mask:0xf
	s_nop 1
	v_add_f32_dpp v33, v32, v32 row_half_mirror row_mask:0xf bank_mask:0xf
	s_nop 1
	v_add_f32_dpp v32, v33, v33 row_mirror row_mask:0xf bank_mask:0xf
	s_nop 0
	v_readlane_b32 s100, v32, 0
	v_readlane_b32 s101, v32, 16
	s_nop 1
	v_mov_b32_e32 v33, s100
	v_add_f32_e32 v33, s101, v33
	v_readlane_b32 s100, v32, 32
	v_readlane_b32 s101, v32, 48
	s_nop 1
	v_add_f32_e32 v33, s100, v33
	v_add_f32_e32 v32, s101, v33
	v_mul_f32_e32 v32, 0x3a800000, v32
	v_add_f32_e32 v32, 0x3727c5ac, v32
	v_rsq_f32_e32 v32, v32
	s_nop 0
	v_pk_mul_f32 v[54:55], v[54:55], v[32:33] op_sel_hi:[1,0]
	v_pk_mul_f32 v[56:57], v[56:57], v[32:33] op_sel_hi:[1,0]
	v_pk_mul_f32 v[58:59], v[58:59], v[32:33] op_sel_hi:[1,0]
	v_pk_mul_f32 v[60:61], v[60:61], v[32:33] op_sel_hi:[1,0]
	v_pk_mul_f32 v[62:63], v[62:63], v[32:33] op_sel_hi:[1,0]
	v_pk_mul_f32 v[64:65], v[64:65], v[32:33] op_sel_hi:[1,0]
	v_pk_mul_f32 v[66:67], v[66:67], v[32:33] op_sel_hi:[1,0]
	v_pk_mul_f32 v[68:69], v[68:69], v[32:33] op_sel_hi:[1,0]
	v_pk_fma_f32 v[54:55], v[0:1], v[54:55], v[4:5]
	v_pk_fma_f32 v[56:57], v[2:3], v[56:57], v[6:7]
	v_pk_fma_f32 v[58:59], v[8:9], v[58:59], v[12:13]
	v_pk_fma_f32 v[60:61], v[10:11], v[60:61], v[14:15]
	v_pk_fma_f32 v[62:63], v[16:17], v[62:63], v[20:21]
	v_pk_fma_f32 v[64:65], v[18:19], v[64:65], v[22:23]
	v_pk_fma_f32 v[66:67], v[24:25], v[66:67], v[28:29]
	v_pk_fma_f32 v[68:69], v[26:27], v[68:69], v[30:31]
	global_store_dwordx4 v[38:39], v[54:57], off
	global_store_dwordx4 v[38:39], v[58:61], off offset:1024
	global_store_dwordx4 v[38:39], v[62:65], off offset:2048
	global_store_dwordx4 v[38:39], v[66:69], off offset:3072
	s_lshl_b32 s100, s99, 1
	s_add_i32 s100, s100, s98
	s_cmp_ge_i32 s100, 0x8400
	s_cbranch_scc1 .Lln4_A_nopf
	s_lshl_b32 s100, s100, 11
	s_mov_b32 s101, 0
	v_lshl_add_u64 v[32:33], v[34:35], 0, s[100:101]
	global_load_dwordx2 v[38:39], v[32:33], off
	global_load_dwordx2 v[40:41], v[32:33], off offset:512
	global_load_dwordx2 v[42:43], v[32:33], off offset:1024
	global_load_dwordx2 v[44:45], v[32:33], off offset:1536

.Lln4_B_go:
	v_lshlrev_b32_e32 v54, 16, v46
	v_and_b32_e32 v55, 0xffff0000, v46
	v_lshlrev_b32_e32 v56, 16, v47
	v_and_b32_e32 v57, 0xffff0000, v47
	v_lshlrev_b32_e32 v58, 16, v48
	v_and_b32_e32 v59, 0xffff0000, v48
	v_lshlrev_b32_e32 v60, 16, v49
	v_and_b32_e32 v61, 0xffff0000, v49
	v_lshlrev_b32_e32 v62, 16, v50
	v_and_b32_e32 v63, 0xffff0000, v50
	v_lshlrev_b32_e32 v64, 16, v51
	v_and_b32_e32 v65, 0xffff0000, v51
	v_lshlrev_b32_e32 v66, 16, v52
	v_and_b32_e32 v67, 0xffff0000, v52
	v_lshlrev_b32_e32 v68, 16, v53
	v_and_b32_e32 v69, 0xffff0000, v53
	s_lshl_b32 s100, s98, 12
	s_mov_b32 s101, 0
	v_lshl_add_u64 v[46:47], v[36:37], 0, s[100:101]
	v_pk_add_f32 v[48:49], v[54:55], v[56:57]
	v_pk_add_f32 v[50:51], v[58:59], v[60:61]
	v_pk_add_f32 v[52:53], v[62:63], v[64:65]
	v_pk_add_f32 v[32:33], v[66:67], v[68:69]
	v_pk_add_f32 v[48:49], v[48:49], v[50:51]
	v_pk_add_f32 v[52:53], v[52:53], v[32:33]
	s_nop 0
	v_pk_add_f32 v[48:49], v[48:49], v[52:53]
	s_nop 0
	v_add_f32_e32 v32, v48, v49
	s_nop 1
	v_add_f32_dpp v33, v32, v32 quad_perm:[1,0,3,2] row_mask:0xf bank_mask:0xf
	s_nop 1
	v_add_f32_dpp v32, v33, v33 quad_perm:[2,3,0,1] row_mask:0xf bank_mask:0xf
	s_nop 1
	v_add_f32_dpp v33, v32, v32 row_half_mirror row_mask:0xf bank_mask:0xf
	s_nop 1
	v_add_f32_dpp v32, v33, v33 row_mirror row_mask:0xf bank_mask:0xf
	s_nop 0
	v_readlane_b32 s100, v32, 0
	v_readlane_b32 s101, v32, 16
	s_nop 1
	v_mov_b32_e32 v33, s100
	v_add_f32_e32 v33, s101, v33
	v_readlane_b32 s100, v32, 32
	v_readlane_b32 s101, v32, 48
	s_nop 1
	v_add_f32_e32 v33, s100, v33
	v_add_f32_e32 v32, s101, v33
	v_mul_f32_e32 v32, 0x3a800000, v32
	v_pk_add_f32 v[54:55], v[54:55], v[32:33] op_sel_hi:[1,0] neg_lo:[0,1] neg_hi:[0,1]
	v_pk_add_f32 v[56:57], v[56:57], v[32:33] op_sel_hi:[1,0] neg_lo:[0,1] neg_hi:[0,1]
	v_pk_add_f32 v[58:59], v[58:59], v[32:33] op_sel_hi:[1,0] neg_lo:[0,1] neg_hi:[0,1]
	v_pk_add_f32 v[60:61], v[60:61], v[32:33] op_sel_hi:[1,0] neg_lo:[0,1] neg_hi:[0,1]
	v_pk_add_f32 v[62:63], v[62:63], v[32:33] op_sel_hi:[1,0] neg_lo:[0,1] neg_hi:[0,1]
	v_pk_add_f32 v[64:65], v[64:65], v[32:33] op_sel_hi:[1,0] neg_lo:[0,1] neg_hi:[0,1]
	v_pk_add_f32 v[66:67], v[66:67], v[32:33] op_sel_hi:[1,0] neg_lo:[0,1] neg_hi:[0,1]
	v_pk_add_f32 v[68:69], v[68:69], v[32:33] op_sel_hi:[1,0] neg_lo:[0,1] neg_hi:[0,1]
	v_pk_mul_f32 v[48:49], v[54:55], v[54:55]
	v_pk_mul_f32 v[50:51], v[56:57], v[56:57]
	v_pk_mul_f32 v[52:53], v[58:59], v[58:59]
	v_pk_fma_f32 v[48:49], v[60:61], v[60:61], v[48:49]
	v_pk_fma_f32 v[50:51], v[62:63], v[62:63], v[50:51]
	v_pk_fma_f32 v[52:53], v[64:65], v[64:65], v[52:53]
	v_pk_fma_f32 v[48:49], v[66:67], v[66:67], v[48:49]
	v_pk_fma_f32 v[50:51], v[68:69], v[68:69], v[50:51]
	v_pk_add_f32 v[48:49], v[48:49], v[52:53]
	s_nop 0
	v_pk_add_f32 v[48:49], v[48:49], v[50:51]
	s_nop 0
	v_add_f32_e32 v32, v48, v49
	s_nop 1
	v_add_f32_dpp v33, v32, v32 quad_perm:[1,0,3,2] row_mask:0xf bank_mask:0xf
	s_nop 1
	v_add_f32_dpp v32, v33, v33 quad_perm:[2,3,0,1] row_mask:0xf bank_mask:0xf
	s_nop 1
	v_add_f32_dpp v33, v32, v32 row_half_mirror row_mask:0xf bank_mask:0xf
	s_nop 1
	v_add_f32_dpp v32, v33, v33 row_mirror row_mask:0xf bank_mask:0xf
	s_nop 0
	v_readlane_b32 s100, v32, 0
	v_readlane_b32 s101, v32, 16
	s_nop 1
	v_mov_b32_e32 v33, s100
	v_add_f32_e32 v33, s101, v33
	v_readlane_b32 s100, v32, 32
	v_readlane_b32 s101, v32, 48
	s_nop 1
	v_add_f32_e32 v33, s100, v33
	v_add_f32_e32 v32, s101, v33
	v_mul_f32_e32 v32, 0x3a800000, v32
	v_add_f32_e32 v32, 0x3727c5ac, v32
	v_rsq_f32_e32 v32, v32
	s_nop 0
	v_pk_mul_f32 v[54:55], v[54:55], v[32:33] op_sel_hi:[1,0]
	v_pk_mul_f32 v[56:57], v[56:57], v[32:33] op_sel_hi:[1,0]
	v_pk_mul_f32 v[58:59], v[58:59], v[32:33] op_sel_hi:[1,0]
	v_pk_mul_f32 v[60:61], v[60:61], v[32:33] op_sel_hi:[1,0]
	v_pk_mul_f32 v[62:63], v[62:63], v[32:33] op_sel_hi:[1,0]
	v_pk_mul_f32 v[64:65], v[64:65], v[32:33] op_sel_hi:[1,0]
	v_pk_mul_f32 v[66:67], v[66:67], v[32:33] op_sel_hi:[1,0]
	v_pk_mul_f32 v[68:69], v[68:69], v[32:33] op_sel_hi:[1,0]
	v_pk_fma_f32 v[54:55], v[0:1], v[54:55], v[4:5]
	v_pk_fma_f32 v[56:57], v[2:3], v[56:57], v[6:7]
	v_pk_fma_f32 v[58:59], v[8:9], v[58:59], v[12:13]
	v_pk_fma_f32 v[60:61], v[10:11], v[60:61], v[14:15]
	v_pk_fma_f32 v[62:63], v[16:17], v[62:63], v[20:21]
	v_pk_fma_f32 v[64:65], v[18:19], v[64:65], v[22:23]
	v_pk_fma_f32 v[66:67], v[24:25], v[66:67], v[28:29]
	v_pk_fma_f32 v[68:69], v[26:27], v[68:69], v[30:31]
	global_store_dwordx4 v[46:47], v[54:57], off
	global_store_dwordx4 v[46:47], v[58:61], off offset:1024
	global_store_dwordx4 v[46:47], v[62:65], off offset:2048
	global_store_dwordx4 v[46:47], v[66:69], off offset:3072
	s_lshl_b32 s100, s99, 1
	s_add_i32 s100, s100, s98
	s_cmp_ge_i32 s100, 0x8400
	s_cbranch_scc1 .Lln4_B_nopf
	s_lshl_b32 s100, s100, 11
	s_mov_b32 s101, 0
	v_lshl_add_u64 v[32:33], v[34:35], 0, s[100:101]
	global_load_dwordx2 v[46:47], v[32:33], off
	global_load_dwordx2 v[48:49], v[32:33], off offset:512
	global_load_dwordx2 v[50:51], v[32:33], off offset:1024
	global_load_dwordx2 v[52:53], v[32:33], off offset:1536

.Lln4_done:
.LBB0_1927:
	s_endpgm

	.amdhsa_kernel mega_fwd
		.amdhsa_group_segment_fixed_size 0
		.amdhsa_private_segment_fixed_size 0
		.amdhsa_kernarg_size 480
		.amdhsa_user_sgpr_count 2
		.amdhsa_user_sgpr_dispatch_ptr 0
		.amdhsa_user_sgpr_queue_ptr 0
		.amdhsa_user_sgpr_kernarg_segment_ptr 1
		.amdhsa_user_sgpr_dispatch_id 0
		.amdhsa_user_sgpr_kernarg_preload_length 0
		.amdhsa_user_sgpr_kernarg_preload_offset 0
		.amdhsa_user_sgpr_private_segment_size 0
		.amdhsa_uses_dynamic_stack 0
		.amdhsa_enable_private_segment 0
		.amdhsa_system_sgpr_workgroup_id_x 1
		.amdhsa_system_sgpr_workgroup_id_y 0
		.amdhsa_system_sgpr_workgroup_id_z 0
		.amdhsa_system_sgpr_workgroup_info 0
		.amdhsa_system_vgpr_workitem_id 2
		.amdhsa_next_free_vgpr 256
		.amdhsa_next_free_sgpr 102
		.amdhsa_accum_offset 256
		.amdhsa_reserve_vcc 1
		.amdhsa_float_round_mode_32 0
		.amdhsa_float_round_mode_16_64 0
		.amdhsa_float_denorm_mode_32 3
		.amdhsa_float_denorm_mode_16_64 3
		.amdhsa_dx10_clamp 1
		.amdhsa_ieee_mode 1
		.amdhsa_fp16_overflow 0
		.amdhsa_tg_split 0
		.amdhsa_exception_fp_ieee_invalid_op 0
		.amdhsa_exception_fp_denorm_src 0
		.amdhsa_exception_fp_ieee_div_zero 0
		.amdhsa_exception_fp_ieee_overflow 0
		.amdhsa_exception_fp_ieee_underflow 0
		.amdhsa_exception_fp_ieee_inexact 0
		.amdhsa_exception_int_div_zero 0
	.end_amdhsa_kernel

amdhsa.kernels:
  - .agpr_count:     0
    .args:
      - .offset:         0
        .size:           224
        .value_kind:     by_value
      - .offset:         224
        .size:           4
        .value_kind:     hidden_block_count_x
      - .offset:         228
        .size:           4
        .value_kind:     hidden_block_count_y
      - .offset:         232
        .size:           4
        .value_kind:     hidden_block_count_z
      - .offset:         236
        .size:           2
        .value_kind:     hidden_group_size_x
      - .offset:         238
        .size:           2
        .value_kind:     hidden_group_size_y
      - .offset:         240
        .size:           2
        .value_kind:     hidden_group_size_z
      - .offset:         242
        .size:           2
        .value_kind:     hidden_remainder_x
      - .offset:         244
        .size:           2
        .value_kind:     hidden_remainder_y
      - .offset:         246
        .size:           2
        .value_kind:     hidden_remainder_z
      - .offset:         264
        .size:           8
        .value_kind:     hidden_global_offset_x
      - .offset:         272
        .size:           8
        .value_kind:     hidden_global_offset_y
      - .offset:         280
        .size:           8
        .value_kind:     hidden_global_offset_z
      - .offset:         288
        .size:           2
        .value_kind:     hidden_grid_dims
      - .offset:         312
        .size:           8
        .value_kind:     hidden_multigrid_sync_arg
      - .offset:         344
        .size:           4
        .value_kind:     hidden_dynamic_lds_size
    .group_segment_fixed_size: 0
    .kernarg_segment_align: 8
    .kernarg_segment_size: 480
    .language:       OpenCL C
    .language_version:
      - 2
      - 0
    .max_flat_workgroup_size: 512
    .name:           mega_fwd
    .private_segment_fixed_size: 0
    .sgpr_count:     108
    .sgpr_spill_count: 49
    .symbol:         mega_fwd.kd
    .uniform_work_group_size: 1
    .uses_dynamic_stack: false
    .vgpr_count:     256
    .vgpr_spill_count: 0
    .wavefront_size: 64
